# phase 3 scan helper wave runs 9 steps ahead of the scan instead of 14 (its prefetched lines are still in L2 when the scan reads them)
# baseline (speedup 1.0000x reference)
; #define PINM do { asm volatile("" ::: "memory"); __builtin_amdgcn_sched_barrier(0); } while (0)
; DI void scan_item(const Params& p, int item, int lane) {
;     ...
;         const int ul = u0 + 127;
;     ...
;         for (int st = 0; st < 125; st += 5) {
;             const int u = u0 + st;
;             scan_step(s0, acc, SST + (size_t)u * 4096, irow, g);       PINM; scan_load(s0, GT, HH, min(u + 5, ul), irow, i16, g); PINM;
;             scan_step(s1, acc, SST + (size_t)(u + 1) * 4096, irow, g); PINM; scan_load(s1, GT, HH, min(u + 6, ul), irow, i16, g); PINM;
;             scan_step(s2, acc, SST + (size_t)(u + 2) * 4096, irow, g); PINM; scan_load(s2, GT, HH, min(u + 7, ul), irow, i16, g); PINM;
;             scan_step(s3, acc, SST + (size_t)(u + 3) * 4096, irow, g); PINM; scan_load(s3, GT, HH, min(u + 8, ul), irow, i16, g); PINM;
;             scan_step(s4, acc, SST + (size_t)(u + 4) * 4096, irow, g); PINM; scan_load(s4, GT, HH, min(u + 9, ul), irow, i16, g); PINM;
;         }
.Lscan_h_loop:
	ds_read_b32 v243, v244
	s_waitcnt lgkmcnt(0)
	v_readfirstlane_b32 s96, v243
	s_add_i32 s96, s96, 9
	s_min_u32 s96, s96, 0x80
